# scan2 solver rewritten with packed FMAs (two columns per instruction)
# speedup vs baseline: 1.0646x; 1.0018x over previous
; #define LAS __attribute__((address_space(3)))
; __device__ __forceinline__ unsigned pk2(float lo, float hi) { const f32x2 v = {lo, hi}; return __builtin_bit_cast(unsigned, __builtin_convertvector(v, bf16x2_t)); }
; __device__ __forceinline__ void scan2_phase(KA a, LAS unsigned char* lds, int G, const int tid, const int bid) {
;     ...
;                 if (mid == 0) {
; #pragma unroll
;                     for (int i = 0; i < 4; ++i) Nf[(4 * fq + i) * 20 + fr] = m[i];
;                 }
;                 else { u32x2 w; w.x = pk2(m[0], m[1]); w.y = pk2(m[2], m[3]); LAS bf16_t* dst = mid == 1 ? MkaT : (mid == 2 ? MbrT : MkrT); *(LAS u32x2*)(dst + fr * 24 + 4 * fq) = w; }
;             }
;             if (mid == 0) {
;                 float acc[16];
; #pragma unroll
;                 for (int tp = 0; tp < 16; ++tp) acc[tp] = (fr == tp) ? 1.0f : 0.f;
; #pragma unroll
;                 for (int s2 = 0; s2 < 15; ++s2) {
;                     const float ts = acc[s2];
; #pragma unroll
;                     for (int q = 0; q < 4; ++q) {
;                         if (4 * q + 3 > s2) {
;                             const f32x4 n4 = *(const LAS f32x4*)(Nf + s2 * 20 + 4 * q);
;                             if (4 * q + 0 > s2) acc[4 * q + 0] += ts * n4.x;
;                             if (4 * q + 1 > s2) acc[4 * q + 1] += ts * n4.y;
;                             if (4 * q + 2 > s2) acc[4 * q + 2] += ts * n4.z;
;                             if (4 * q + 3 > s2) acc[4 * q + 3] += ts * n4.w;
;                         }
;                     }
;                 }
;                 if (fq == 0) {
; #pragma unroll
;                     for (int tp = 0; tp < 16; ++tp) TTf[tp * 20 + fr] = acc[tp];
;                 }
.LBB0_187:
.LBB0_188:
	v_lshl_add_u32 v16, v76, 2, s84
	v_add_u32_e32 v22, v16, v95
	ds_write_b32 v22, v21 offset:20736
	v_add_u32_e32 v21, v16, v96
	v_add_u32_e32 v22, 0x5000, v21
	ds_write2_b32 v22, v17, v18 offset0:64 offset1:84
	ds_write_b32 v21, v20 offset:20896
	s_and_saveexec_b64 s[62:63], s[10:11]
	s_cbranch_execz .LBB0_179
	v_mov_b32_e32 v133, s84
	ds_read_b128 v[20:23], v133 offset:20736
	ds_read_b128 v[24:27], v133 offset:20752
	ds_read_b128 v[28:31], v133 offset:20768
	ds_read_b128 v[32:35], v133 offset:20784
	ds_read_b128 v[36:39], v133 offset:20816
	ds_read_b128 v[40:43], v133 offset:20832
	ds_read_b128 v[44:47], v133 offset:20848
	ds_read_b128 v[48:51], v133 offset:20864
	ds_read_b128 v[52:55], v133 offset:20896
	ds_read_b128 v[56:59], v133 offset:20912
	ds_read_b128 v[60:63], v133 offset:20928
	ds_read_b128 v[64:67], v133 offset:20944
	ds_read_b128 v[68:71], v133 offset:20992
	ds_read_b128 v[72:75], v133 offset:21008
	ds_read_b128 v[200:203], v133 offset:21024
	s_waitcnt lgkmcnt(11)
	v_mov_b32_e32 v182, v97
	v_fma_f32 v183, v97, v21, v98
	v_fma_f32 v184, v97, v22, v99
	v_fma_f32 v185, v97, v23, v100
	v_fma_f32 v186, v97, v24, v101
	v_fma_f32 v187, v97, v25, v102
	v_fma_f32 v188, v97, v26, v103
	v_fma_f32 v189, v97, v27, v104
	v_fma_f32 v190, v97, v28, v105
	v_fma_f32 v191, v97, v29, v106
	v_fma_f32 v192, v97, v30, v107
	v_fma_f32 v193, v97, v31, v108
	v_fma_f32 v194, v97, v32, v109
	v_fma_f32 v195, v97, v33, v110
	v_fma_f32 v196, v97, v34, v111
	v_fma_f32 v197, v97, v35, v112
	ds_read_b128 v[204:207], v133 offset:21072
	ds_read_b128 v[208:211], v133 offset:21088
	ds_read_b128 v[212:215], v133 offset:21104
	ds_read_b128 v[216:219], v133 offset:21152
	s_waitcnt lgkmcnt(11)
	v_pk_fma_f32 v[184:185], v[38:39], v[182:183], v[184:185] op_sel:[0,1,0] op_sel_hi:[1,1,1]
	v_pk_fma_f32 v[186:187], v[40:41], v[182:183], v[186:187] op_sel:[0,1,0] op_sel_hi:[1,1,1]
	v_pk_fma_f32 v[188:189], v[42:43], v[182:183], v[188:189] op_sel:[0,1,0] op_sel_hi:[1,1,1]
	v_pk_fma_f32 v[190:191], v[44:45], v[182:183], v[190:191] op_sel:[0,1,0] op_sel_hi:[1,1,1]
	v_pk_fma_f32 v[192:193], v[46:47], v[182:183], v[192:193] op_sel:[0,1,0] op_sel_hi:[1,1,1]
	v_pk_fma_f32 v[194:195], v[48:49], v[182:183], v[194:195] op_sel:[0,1,0] op_sel_hi:[1,1,1]
	v_pk_fma_f32 v[196:197], v[50:51], v[182:183], v[196:197] op_sel:[0,1,0] op_sel_hi:[1,1,1]
	ds_read_b128 v[220:223], v133 offset:21168
	ds_read_b128 v[224:227], v133 offset:21184
	ds_read_b128 v[20:23], v133 offset:21232
	ds_read_b128 v[24:27], v133 offset:21248
	s_waitcnt lgkmcnt(11)
	v_fmac_f32_e32 v185, v184, v55
	v_pk_fma_f32 v[186:187], v[56:57], v[184:185], v[186:187] op_sel_hi:[1,0,1]
	v_pk_fma_f32 v[188:189], v[58:59], v[184:185], v[188:189] op_sel_hi:[1,0,1]
	v_pk_fma_f32 v[190:191], v[60:61], v[184:185], v[190:191] op_sel_hi:[1,0,1]
	v_pk_fma_f32 v[192:193], v[62:63], v[184:185], v[192:193] op_sel_hi:[1,0,1]
	v_pk_fma_f32 v[194:195], v[64:65], v[184:185], v[194:195] op_sel_hi:[1,0,1]
	v_pk_fma_f32 v[196:197], v[66:67], v[184:185], v[196:197] op_sel_hi:[1,0,1]
	ds_read_b128 v[28:31], v133 offset:21264
	ds_read_b128 v[32:35], v133 offset:21328
	ds_read_b128 v[36:39], v133 offset:21344
	ds_read_b128 v[40:43], v133 offset:21408
	s_waitcnt lgkmcnt(12)
	v_pk_fma_f32 v[186:187], v[68:69], v[184:185], v[186:187] op_sel:[0,1,0] op_sel_hi:[1,1,1]
	v_pk_fma_f32 v[188:189], v[70:71], v[184:185], v[188:189] op_sel:[0,1,0] op_sel_hi:[1,1,1]
	v_pk_fma_f32 v[190:191], v[72:73], v[184:185], v[190:191] op_sel:[0,1,0] op_sel_hi:[1,1,1]
	v_pk_fma_f32 v[192:193], v[74:75], v[184:185], v[192:193] op_sel:[0,1,0] op_sel_hi:[1,1,1]
	v_pk_fma_f32 v[194:195], v[200:201], v[184:185], v[194:195] op_sel:[0,1,0] op_sel_hi:[1,1,1]
	v_pk_fma_f32 v[196:197], v[202:203], v[184:185], v[196:197] op_sel:[0,1,0] op_sel_hi:[1,1,1]
	ds_read_b128 v[44:47], v133 offset:21424
	ds_read_b128 v[48:51], v133 offset:21488
	ds_read_b128 v[52:55], v133 offset:21504
	s_waitcnt lgkmcnt(12)
; #define LAS __attribute__((address_space(3)))
; __device__ __forceinline__ void scan2_phase(KA a, LAS unsigned char* lds, int G, const int tid, const int bid) {
;     ...
; #pragma unroll
;                 for (int s2 = 0; s2 < 15; ++s2) {
;                     const float ts = acc[s2];
; #pragma unroll
;                     for (int q = 0; q < 4; ++q) {
;                         if (4 * q + 3 > s2) {
;                             const f32x4 n4 = *(const LAS f32x4*)(Nf + s2 * 20 + 4 * q);
;                             if (4 * q + 0 > s2) acc[4 * q + 0] += ts * n4.x;
;                             if (4 * q + 1 > s2) acc[4 * q + 1] += ts * n4.y;
;                             if (4 * q + 2 > s2) acc[4 * q + 2] += ts * n4.z;
;                             if (4 * q + 3 > s2) acc[4 * q + 3] += ts * n4.w;
;                         }
;                     }
;                 }
;                 if (fq == 0) {
; #pragma unroll
;                     for (int tp = 0; tp < 16; ++tp) TTf[tp * 20 + fr] = acc[tp];
;                 }
	v_fmac_f32_e32 v187, v186, v205
	v_pk_fma_f32 v[188:189], v[206:207], v[186:187], v[188:189] op_sel_hi:[1,0,1]
	v_pk_fma_f32 v[190:191], v[208:209], v[186:187], v[190:191] op_sel_hi:[1,0,1]
	v_pk_fma_f32 v[192:193], v[210:211], v[186:187], v[192:193] op_sel_hi:[1,0,1]
	v_pk_fma_f32 v[194:195], v[212:213], v[186:187], v[194:195] op_sel_hi:[1,0,1]
	v_pk_fma_f32 v[196:197], v[214:215], v[186:187], v[196:197] op_sel_hi:[1,0,1]
	ds_read_b128 v[56:59], v133 offset:21568
	ds_read_b128 v[60:63], v133 offset:21584
	ds_read_b128 v[64:67], v133 offset:21664
	s_waitcnt lgkmcnt(12)
	v_pk_fma_f32 v[188:189], v[218:219], v[186:187], v[188:189] op_sel:[0,1,0] op_sel_hi:[1,1,1]
	v_pk_fma_f32 v[190:191], v[220:221], v[186:187], v[190:191] op_sel:[0,1,0] op_sel_hi:[1,1,1]
	v_pk_fma_f32 v[192:193], v[222:223], v[186:187], v[192:193] op_sel:[0,1,0] op_sel_hi:[1,1,1]
	v_pk_fma_f32 v[194:195], v[224:225], v[186:187], v[194:195] op_sel:[0,1,0] op_sel_hi:[1,1,1]
	v_pk_fma_f32 v[196:197], v[226:227], v[186:187], v[196:197] op_sel:[0,1,0] op_sel_hi:[1,1,1]
	ds_read_b128 v[68:71], v133 offset:21744
	ds_read_b128 v[72:75], v133 offset:21824
	ds_read_b128 v[200:203], v133 offset:21904
	s_waitcnt lgkmcnt(12)
	v_fmac_f32_e32 v189, v188, v23
	v_pk_fma_f32 v[190:191], v[24:25], v[188:189], v[190:191] op_sel_hi:[1,0,1]
	v_pk_fma_f32 v[192:193], v[26:27], v[188:189], v[192:193] op_sel_hi:[1,0,1]
	v_pk_fma_f32 v[194:195], v[28:29], v[188:189], v[194:195] op_sel_hi:[1,0,1]
	v_pk_fma_f32 v[196:197], v[30:31], v[188:189], v[196:197] op_sel_hi:[1,0,1]
	s_waitcnt lgkmcnt(10)
	v_pk_fma_f32 v[190:191], v[32:33], v[188:189], v[190:191] op_sel:[0,1,0] op_sel_hi:[1,1,1]
	v_pk_fma_f32 v[192:193], v[34:35], v[188:189], v[192:193] op_sel:[0,1,0] op_sel_hi:[1,1,1]
	v_pk_fma_f32 v[194:195], v[36:37], v[188:189], v[194:195] op_sel:[0,1,0] op_sel_hi:[1,1,1]
	v_pk_fma_f32 v[196:197], v[38:39], v[188:189], v[196:197] op_sel:[0,1,0] op_sel_hi:[1,1,1]
	s_waitcnt lgkmcnt(8)
	v_fmac_f32_e32 v191, v190, v41
	v_pk_fma_f32 v[192:193], v[42:43], v[190:191], v[192:193] op_sel_hi:[1,0,1]
	v_pk_fma_f32 v[194:195], v[44:45], v[190:191], v[194:195] op_sel_hi:[1,0,1]
	v_pk_fma_f32 v[196:197], v[46:47], v[190:191], v[196:197] op_sel_hi:[1,0,1]
	s_waitcnt lgkmcnt(6)
	v_pk_fma_f32 v[192:193], v[50:51], v[190:191], v[192:193] op_sel:[0,1,0] op_sel_hi:[1,1,1]
	v_pk_fma_f32 v[194:195], v[52:53], v[190:191], v[194:195] op_sel:[0,1,0] op_sel_hi:[1,1,1]
	v_pk_fma_f32 v[196:197], v[54:55], v[190:191], v[196:197] op_sel:[0,1,0] op_sel_hi:[1,1,1]
	s_waitcnt lgkmcnt(4)
	v_fmac_f32_e32 v193, v192, v59
	v_pk_fma_f32 v[194:195], v[60:61], v[192:193], v[194:195] op_sel_hi:[1,0,1]
	v_pk_fma_f32 v[196:197], v[62:63], v[192:193], v[196:197] op_sel_hi:[1,0,1]
	s_waitcnt lgkmcnt(3)
	v_pk_fma_f32 v[194:195], v[64:65], v[192:193], v[194:195] op_sel:[0,1,0] op_sel_hi:[1,1,1]
	v_pk_fma_f32 v[196:197], v[66:67], v[192:193], v[196:197] op_sel:[0,1,0] op_sel_hi:[1,1,1]
	s_waitcnt lgkmcnt(2)
	v_fmac_f32_e32 v195, v194, v69
	v_pk_fma_f32 v[196:197], v[70:71], v[194:195], v[196:197] op_sel_hi:[1,0,1]
	s_waitcnt lgkmcnt(1)
	v_pk_fma_f32 v[196:197], v[74:75], v[194:195], v[196:197] op_sel:[0,1,0] op_sel_hi:[1,1,1]
	s_waitcnt lgkmcnt(0)
	v_fmac_f32_e32 v197, v196, v203
	v_lshl_add_u32 v198, v76, 2, s84
	v_add_u32_e32 v199, 0x5800, v198
	v_add_u32_e32 v198, 0x5600, v198
	ds_write2_b32 v198, v182, v183 offset0:0 offset1:20
	ds_write2_b32 v198, v184, v185 offset0:40 offset1:60
	ds_write2_b32 v198, v186, v187 offset0:80 offset1:100
	ds_write2_b32 v198, v188, v189 offset0:120 offset1:140
	ds_write2_b32 v198, v190, v191 offset0:160 offset1:180
	ds_write2_b32 v198, v192, v193 offset0:200 offset1:220
	ds_write2_b32 v199, v194, v195 offset0:112 offset1:132
	ds_write2_b32 v199, v196, v197 offset0:152 offset1:172
	s_branch .LBB0_179
